# attention: the 80 packed v_pk_mul_f32 (lazy O rescale) split into scalar v_mul_f32 pairs (bit-identical); on top of all13
# speedup vs baseline: 1.0007x; 1.0007x over previous
.LBB0_1548:
	s_waitcnt lgkmcnt(14)
	v_mfma_f32_32x32x16_bf16 v[32:47], v[156:159], v[192:195], v[32:47]
	v_exp_f32_e32 v112, v112
	v_exp_f32_e32 v113, v113
	v_exp_f32_e32 v114, v114
	v_exp_f32_e32 v115, v115
	s_waitcnt lgkmcnt(12)
	v_mfma_f32_32x32x16_bf16 v[16:31], v[156:159], v[188:191], v[16:31]
	v_exp_f32_e32 v116, v116
	v_exp_f32_e32 v117, v117
	v_exp_f32_e32 v118, v118
	v_exp_f32_e32 v119, v119
	v_add_u32_e32 v0, s38, v220
	ds_read_b128 v[64:67], v0
	ds_read_b128 v[160:163], v0 offset:512
	s_waitcnt lgkmcnt(12)
	v_mfma_f32_32x32x16_bf16 v[32:47], v[152:155], v[184:187], v[32:47]
	v_exp_f32_e32 v120, v120
	v_exp_f32_e32 v121, v121
	v_exp_f32_e32 v122, v122
	v_exp_f32_e32 v123, v123
	ds_read_b128 v[192:195], v0 offset:2048
	ds_read_b128 v[184:187], v0 offset:2560
	s_waitcnt lgkmcnt(12)
	v_mfma_f32_32x32x16_bf16 v[16:31], v[152:155], v[84:87], v[16:31]
	v_exp_f32_e32 v124, v124
	v_exp_f32_e32 v125, v125
	v_exp_f32_e32 v126, v126
	v_exp_f32_e32 v127, v127
	ds_read_b128 v[188:191], v0 offset:4096
	ds_read_b128 v[176:179], v0 offset:4608
	s_waitcnt lgkmcnt(12)
	v_mfma_f32_32x32x16_bf16 v[32:47], v[144:147], v[80:83], v[32:47]
	v_exp_f32_e32 v96, v96
	v_exp_f32_e32 v97, v97
	v_exp_f32_e32 v98, v98
	v_exp_f32_e32 v99, v99
	ds_read_b128 v[180:183], v0 offset:6144
	ds_read_b128 v[172:175], v0 offset:6656
	s_waitcnt lgkmcnt(12)
	v_mfma_f32_32x32x16_bf16 v[16:31], v[144:147], v[10:13], v[16:31]
	v_exp_f32_e32 v100, v100
	v_exp_f32_e32 v101, v101
	v_exp_f32_e32 v102, v102
	v_exp_f32_e32 v103, v103
	s_waitcnt lgkmcnt(10)
	v_mfma_f32_32x32x16_bf16 v[32:47], v[136:139], v[6:9], v[32:47]
	v_exp_f32_e32 v104, v104
	v_exp_f32_e32 v105, v105
	v_exp_f32_e32 v106, v106
	v_exp_f32_e32 v107, v107
	s_waitcnt lgkmcnt(8)
	v_mfma_f32_32x32x16_bf16 v[16:31], v[136:139], v[2:5], v[16:31]
	v_exp_f32_e32 v108, v108
	v_exp_f32_e32 v109, v109
	v_exp_f32_e32 v110, v110
	v_exp_f32_e32 v111, v111
	s_waitcnt vmcnt(2) lgkmcnt(0)
	s_barrier
	s_andn2_b64 vcc, exec, s[8:9]
	v_add_u32_e32 v0, s48, v222
	s_cbranch_vccnz .LBB0_1550
	s_waitcnt lgkmcnt(0)
	ds_read_b128 v[2:5], v0 offset:49248
	ds_read_b128 v[6:9], v0 offset:49216
	ds_read_b128 v[10:13], v0 offset:49184
	ds_read_b128 v[68:71], v0 offset:49152
	s_waitcnt lgkmcnt(3)
	v_mul_f32_e32 v44, v44, v2
	v_mul_f32_e32 v45, v45, v3
	s_waitcnt lgkmcnt(2)
	v_mul_f32_e32 v40, v40, v6
	v_mul_f32_e32 v41, v41, v7
	s_waitcnt lgkmcnt(1)
	v_mul_f32_e32 v36, v36, v10
	v_mul_f32_e32 v37, v37, v11
	v_mul_f32_e32 v46, v46, v4
	v_mul_f32_e32 v47, v47, v5
	v_mul_f32_e32 v42, v42, v8
	v_mul_f32_e32 v43, v43, v9
	v_mul_f32_e32 v38, v38, v12
	v_mul_f32_e32 v39, v39, v13
	s_waitcnt lgkmcnt(0)
	v_mul_f32_e32 v34, v34, v70
	v_mul_f32_e32 v35, v35, v71
	v_mul_f32_e32 v32, v32, v68
	v_mul_f32_e32 v33, v33, v69
	v_mul_f32_e32 v28, v28, v2
	v_mul_f32_e32 v29, v29, v3
	v_mul_f32_e32 v24, v24, v6
	v_mul_f32_e32 v25, v25, v7
	v_mul_f32_e32 v20, v20, v10
	v_mul_f32_e32 v21, v21, v11
	v_mul_f32_e32 v30, v30, v4
	v_mul_f32_e32 v31, v31, v5
	v_mul_f32_e32 v26, v26, v8
	v_mul_f32_e32 v27, v27, v9
	v_mul_f32_e32 v22, v22, v12
	v_mul_f32_e32 v23, v23, v13
	v_mul_f32_e32 v18, v18, v70
	v_mul_f32_e32 v19, v19, v71
	v_mul_f32_e32 v16, v16, v68
	v_mul_f32_e32 v17, v17, v69

.LBB0_1551:
	s_waitcnt lgkmcnt(14)
	v_mfma_f32_32x32x16_bf16 v[32:47], v[156:159], v[168:171], v[32:47]
	v_exp_f32_e32 v80, v80
	v_exp_f32_e32 v81, v81
	v_exp_f32_e32 v82, v82
	v_exp_f32_e32 v83, v83
	s_waitcnt lgkmcnt(12)
	v_mfma_f32_32x32x16_bf16 v[16:31], v[156:159], v[164:167], v[16:31]
	v_exp_f32_e32 v84, v84
	v_exp_f32_e32 v85, v85
	v_exp_f32_e32 v86, v86
	v_exp_f32_e32 v87, v87
	v_add_u32_e32 v14, s13, v220
	ds_read_b128 v[188:191], v14
	ds_read_b128 v[184:187], v14 offset:512
	s_waitcnt lgkmcnt(12)
	v_mfma_f32_32x32x16_bf16 v[32:47], v[152:155], v[160:163], v[32:47]
	v_exp_f32_e32 v88, v88
	v_exp_f32_e32 v89, v89
	v_exp_f32_e32 v90, v90
	v_exp_f32_e32 v91, v91
	ds_read_b128 v[180:183], v14 offset:2048
	ds_read_b128 v[176:179], v14 offset:2560
	s_waitcnt lgkmcnt(12)
	v_mfma_f32_32x32x16_bf16 v[16:31], v[152:155], v[116:119], v[16:31]
	v_exp_f32_e32 v92, v92
	v_exp_f32_e32 v93, v93
	v_exp_f32_e32 v94, v94
	v_exp_f32_e32 v95, v95
	ds_read_b128 v[172:175], v14 offset:4096
	ds_read_b128 v[168:171], v14 offset:4608
	s_waitcnt lgkmcnt(12)
	v_mfma_f32_32x32x16_bf16 v[32:47], v[144:147], v[112:115], v[32:47]
	v_exp_f32_e32 v64, v64
	v_exp_f32_e32 v65, v65
	v_exp_f32_e32 v66, v66
	v_exp_f32_e32 v67, v67
	ds_read_b128 v[164:167], v14 offset:6144
	ds_read_b128 v[160:163], v14 offset:6656
	s_waitcnt lgkmcnt(12)
	v_mfma_f32_32x32x16_bf16 v[16:31], v[144:147], v[10:13], v[16:31]
	v_exp_f32_e32 v68, v68
	v_exp_f32_e32 v69, v69
	v_exp_f32_e32 v70, v70
	v_exp_f32_e32 v71, v71
	s_waitcnt lgkmcnt(10)
	v_mfma_f32_32x32x16_bf16 v[32:47], v[136:139], v[6:9], v[32:47]
	v_exp_f32_e32 v72, v72
	v_exp_f32_e32 v73, v73
	v_exp_f32_e32 v74, v74
	v_exp_f32_e32 v75, v75
	s_waitcnt lgkmcnt(8)
	v_mfma_f32_32x32x16_bf16 v[16:31], v[136:139], v[2:5], v[16:31]
	v_exp_f32_e32 v76, v76
	v_exp_f32_e32 v77, v77
	v_exp_f32_e32 v78, v78
	v_exp_f32_e32 v79, v79
	s_waitcnt vmcnt(2) lgkmcnt(0)
	s_barrier
	s_andn2_b64 vcc, exec, s[8:9]
	s_cbranch_vccnz .LBB0_1553
	s_waitcnt lgkmcnt(0)
	ds_read_b128 v[2:5], v0 offset:49248
	ds_read_b128 v[6:9], v0 offset:49216
	ds_read_b128 v[10:13], v0 offset:49184
	ds_read_b128 v[96:99], v0 offset:49152
	s_waitcnt lgkmcnt(3)
	v_mul_f32_e32 v44, v44, v2
	v_mul_f32_e32 v45, v45, v3
	s_waitcnt lgkmcnt(2)
	v_mul_f32_e32 v40, v40, v6
	v_mul_f32_e32 v41, v41, v7
	s_waitcnt lgkmcnt(1)
	v_mul_f32_e32 v36, v36, v10
	v_mul_f32_e32 v37, v37, v11
	v_mul_f32_e32 v46, v46, v4
	v_mul_f32_e32 v47, v47, v5
	v_mul_f32_e32 v42, v42, v8
	v_mul_f32_e32 v43, v43, v9
	v_mul_f32_e32 v38, v38, v12
	v_mul_f32_e32 v39, v39, v13
	s_waitcnt lgkmcnt(0)
	v_mul_f32_e32 v34, v34, v98
	v_mul_f32_e32 v35, v35, v99
	v_mul_f32_e32 v32, v32, v96
	v_mul_f32_e32 v33, v33, v97
	v_mul_f32_e32 v28, v28, v2
	v_mul_f32_e32 v29, v29, v3
	v_mul_f32_e32 v24, v24, v6
	v_mul_f32_e32 v25, v25, v7
	v_mul_f32_e32 v20, v20, v10
	v_mul_f32_e32 v21, v21, v11
	v_mul_f32_e32 v30, v30, v4
	v_mul_f32_e32 v31, v31, v5
	v_mul_f32_e32 v26, v26, v8
	v_mul_f32_e32 v27, v27, v9
	v_mul_f32_e32 v22, v22, v12
	v_mul_f32_e32 v23, v23, v13
	v_mul_f32_e32 v18, v18, v98
	v_mul_f32_e32 v19, v19, v99
	v_mul_f32_e32 v16, v16, v96
	v_mul_f32_e32 v17, v17, v97

.LBB0_1564:
	s_waitcnt lgkmcnt(14)
	v_mfma_f32_32x32x16_bf16 v[32:47], v[156:159], v[192:195], v[32:47]
	v_exp_f32_e32 v64, v64
	v_exp_f32_e32 v65, v65
	v_exp_f32_e32 v66, v66
	v_exp_f32_e32 v67, v67
	s_waitcnt lgkmcnt(12)
	v_mfma_f32_32x32x16_bf16 v[16:31], v[156:159], v[124:127], v[16:31]
	v_exp_f32_e32 v68, v68
	v_exp_f32_e32 v69, v69
	v_exp_f32_e32 v70, v70
	v_exp_f32_e32 v71, v71
	s_waitcnt lgkmcnt(10)
	v_mfma_f32_32x32x16_bf16 v[32:47], v[152:155], v[120:123], v[32:47]
	v_exp_f32_e32 v72, v72
	v_exp_f32_e32 v73, v73
	v_exp_f32_e32 v74, v74
	v_exp_f32_e32 v75, v75
	s_waitcnt lgkmcnt(8)
	v_mfma_f32_32x32x16_bf16 v[16:31], v[152:155], v[116:119], v[16:31]
	v_exp_f32_e32 v76, v76
	v_exp_f32_e32 v77, v77
	v_exp_f32_e32 v78, v78
	v_exp_f32_e32 v79, v79
	s_waitcnt lgkmcnt(6)
	v_mfma_f32_32x32x16_bf16 v[32:47], v[144:147], v[112:115], v[32:47]
	v_exp_f32_e32 v48, v48
	v_exp_f32_e32 v49, v49
	v_exp_f32_e32 v50, v50
	v_exp_f32_e32 v51, v51
	s_waitcnt lgkmcnt(4)
	v_mfma_f32_32x32x16_bf16 v[16:31], v[144:147], v[10:13], v[16:31]
	v_exp_f32_e32 v52, v52
	v_exp_f32_e32 v53, v53
	v_exp_f32_e32 v54, v54
	v_exp_f32_e32 v55, v55
	s_waitcnt lgkmcnt(2)
	v_mfma_f32_32x32x16_bf16 v[32:47], v[136:139], v[6:9], v[32:47]
	v_exp_f32_e32 v56, v56
	v_exp_f32_e32 v57, v57
	v_exp_f32_e32 v58, v58
	v_exp_f32_e32 v59, v59
	s_waitcnt lgkmcnt(0)
	v_mfma_f32_32x32x16_bf16 v[16:31], v[136:139], v[2:5], v[16:31]
	v_exp_f32_e32 v60, v60
	v_exp_f32_e32 v61, v61
	v_exp_f32_e32 v62, v62
	v_exp_f32_e32 v63, v63
	s_andn2_b64 vcc, exec, s[6:7]
	v_lshl_add_u32 v2, v216, 2, s48
	s_cbranch_vccnz .LBB0_1566
	s_waitcnt lgkmcnt(0)
	ds_read_b128 v[4:7], v2 offset:49248
	ds_read_b128 v[8:11], v2 offset:49216
	ds_read_b128 v[12:15], v2 offset:49184
	ds_read_b128 v[80:83], v2 offset:49152
	s_waitcnt lgkmcnt(3)
	v_mul_f32_e32 v46, v46, v6
	v_mul_f32_e32 v47, v47, v7
	s_waitcnt lgkmcnt(2)
	v_mul_f32_e32 v42, v42, v10
	v_mul_f32_e32 v43, v43, v11
	s_waitcnt lgkmcnt(1)
	v_mul_f32_e32 v38, v38, v14
	v_mul_f32_e32 v39, v39, v15
	s_waitcnt lgkmcnt(0)
	v_mul_f32_e32 v34, v34, v82
	v_mul_f32_e32 v35, v35, v83
	v_mul_f32_e32 v44, v44, v4
	v_mul_f32_e32 v45, v45, v5
	v_mul_f32_e32 v40, v40, v8
	v_mul_f32_e32 v41, v41, v9
	v_mul_f32_e32 v36, v36, v12
	v_mul_f32_e32 v37, v37, v13
	v_mul_f32_e32 v32, v32, v80
	v_mul_f32_e32 v33, v33, v81
	v_mul_f32_e32 v30, v30, v6
	v_mul_f32_e32 v31, v31, v7
	v_mul_f32_e32 v26, v26, v10
	v_mul_f32_e32 v27, v27, v11
	v_mul_f32_e32 v22, v22, v14
	v_mul_f32_e32 v23, v23, v15
	v_mul_f32_e32 v18, v18, v82
	v_mul_f32_e32 v19, v19, v83
	v_mul_f32_e32 v28, v28, v4
	v_mul_f32_e32 v29, v29, v5
	v_mul_f32_e32 v24, v24, v8
	v_mul_f32_e32 v25, v25, v9
	v_mul_f32_e32 v20, v20, v12
	v_mul_f32_e32 v21, v21, v13
	v_mul_f32_e32 v16, v16, v80
	v_mul_f32_e32 v17, v17, v81

.LBB0_1582:
	s_waitcnt lgkmcnt(0)
	ds_read_b128 v[2:5], v253 offset:49248
	ds_read_b128 v[6:9], v253 offset:49216
	ds_read_b128 v[10:13], v253 offset:49184
	ds_read_b128 v[64:67], v253 offset:49152
	s_waitcnt lgkmcnt(3)
	v_mul_f32_e32 v44, v44, v2
	v_mul_f32_e32 v45, v45, v3
	s_waitcnt lgkmcnt(2)
	v_mul_f32_e32 v40, v40, v6
	v_mul_f32_e32 v41, v41, v7
	s_waitcnt lgkmcnt(1)
	v_mul_f32_e32 v36, v36, v10
	v_mul_f32_e32 v37, v37, v11
	v_mul_f32_e32 v46, v46, v4
	v_mul_f32_e32 v47, v47, v5
	v_mul_f32_e32 v42, v42, v8
	v_mul_f32_e32 v43, v43, v9
	v_mul_f32_e32 v38, v38, v12
	v_mul_f32_e32 v39, v39, v13
	s_waitcnt lgkmcnt(0)
	v_mul_f32_e32 v34, v34, v66
	v_mul_f32_e32 v35, v35, v67
	v_mul_f32_e32 v32, v32, v64
	v_mul_f32_e32 v33, v33, v65
	v_mul_f32_e32 v28, v28, v2
	v_mul_f32_e32 v29, v29, v3
	v_mul_f32_e32 v24, v24, v6
	v_mul_f32_e32 v25, v25, v7
	v_mul_f32_e32 v20, v20, v10
	v_mul_f32_e32 v21, v21, v11
	v_mul_f32_e32 v30, v30, v4
	v_mul_f32_e32 v31, v31, v5
	v_mul_f32_e32 v26, v26, v8
	v_mul_f32_e32 v27, v27, v9
	v_mul_f32_e32 v22, v22, v12
	v_mul_f32_e32 v23, v23, v13
	v_mul_f32_e32 v18, v18, v66
	v_mul_f32_e32 v19, v19, v67
	v_mul_f32_e32 v16, v16, v64
	v_mul_f32_e32 v17, v17, v65

.LBB0_1605:
	s_waitcnt lgkmcnt(0)
	ds_read_b128 v[2:5], v253 offset:49248
	ds_read_b128 v[6:9], v253 offset:49216
	ds_read_b128 v[10:13], v253 offset:49184
	ds_read_b128 v[96:99], v253 offset:49152
	s_waitcnt lgkmcnt(3)
	v_mul_f32_e32 v44, v44, v2
	v_mul_f32_e32 v45, v45, v3
	s_waitcnt lgkmcnt(2)
	v_mul_f32_e32 v40, v40, v6
	v_mul_f32_e32 v41, v41, v7
	s_waitcnt lgkmcnt(1)
	v_mul_f32_e32 v36, v36, v10
	v_mul_f32_e32 v37, v37, v11
	v_mul_f32_e32 v46, v46, v4
	v_mul_f32_e32 v47, v47, v5
	v_mul_f32_e32 v42, v42, v8
	v_mul_f32_e32 v43, v43, v9
	v_mul_f32_e32 v38, v38, v12
	v_mul_f32_e32 v39, v39, v13
	s_waitcnt lgkmcnt(0)
	v_mul_f32_e32 v34, v34, v98
	v_mul_f32_e32 v35, v35, v99
	v_mul_f32_e32 v32, v32, v96
	v_mul_f32_e32 v33, v33, v97
	v_mul_f32_e32 v28, v28, v2
	v_mul_f32_e32 v29, v29, v3
	v_mul_f32_e32 v24, v24, v6
	v_mul_f32_e32 v25, v25, v7
	v_mul_f32_e32 v20, v20, v10
	v_mul_f32_e32 v21, v21, v11
	v_mul_f32_e32 v30, v30, v4
	v_mul_f32_e32 v31, v31, v5
	v_mul_f32_e32 v26, v26, v8
	v_mul_f32_e32 v27, v27, v9
	v_mul_f32_e32 v22, v22, v12
	v_mul_f32_e32 v23, v23, v13
	v_mul_f32_e32 v18, v18, v98
	v_mul_f32_e32 v19, v19, v99
	v_mul_f32_e32 v16, v16, v96
	v_mul_f32_e32 v17, v17, v97
